# mixer: dynamic pair queue (atomic + LDS broadcast + 2 barriers per claim) replaced by the equivalent static schedule derived from (blockIdx, step)
# speedup vs baseline: 1.0013x; 1.0013x over previous
.LBB0_225:
	s_mov_b64 s[52:53], 0x8000
	s_andn2_b64 vcc, exec, s[0:1]
	s_cbranch_vccnz .LBB0_462
	v_mov_b32_e32 v250, 0
	v_readfirstlane_b32 s4, v160
	s_lshr_b32 s77, s4, 8
	s_lshl_b32 s0, s77, 16
	s_add_i32 s78, s0, 0
	v_readlane_b32 s0, v254, 34
	v_readlane_b32 s1, v254, 35
	s_mov_b32 s10, s0
	s_lshl_b32 s0, s0, 6
	s_ashr_i32 s1, s0, 31
	s_lshl_b64 s[0:1], s[0:1], 2
	v_readlane_b32 s8, v254, 43
	v_readlane_b32 s9, v254, 44
	s_add_u32 s0, s8, s0
	s_addc_u32 s1, s9, s1
	s_add_u32 s56, s0, 0x17bcd840
	s_addc_u32 s57, s1, 0
	s_lshr_b32 s0, s4, 1
	s_and_b32 s0, s0, 0x80
	v_writelane_b32 v254, s0, 59
	s_lshl_b32 s0, s10, 2
	s_bfe_u32 s5, s4, 0x10008
	v_writelane_b32 v254, s0, 60
	s_lshl_b32 s1, s10, 9
	s_lshl_b32 s0, s5, 8
	s_or_b32 s0, s0, s1
	s_lshl_b32 s60, s10, 1
	v_writelane_b32 v254, s1, 61
	s_ashr_i32 s1, s0, 31
	s_cmp_eq_u32 s5, 0
	s_cselect_b64 s[36:37], -1, 0
	s_lshl_b32 s12, s5, 2
	s_mov_b32 s13, s93
	s_ashr_i32 s11, s10, 31
	v_writelane_b32 v254, s12, 62
	s_bitcmp1_b32 s4, 8
	s_mul_i32 s6, s5, 0xa00000
	v_writelane_b32 v254, s13, 63
	s_cselect_b64 s[12:13], -1, 0
	v_writelane_b32 v254, s10, 34
	s_lshl_b64 s[58:59], s[10:11], 1
	s_add_u32 s62, s8, 0x664a000
	s_addc_u32 s63, s9, 0
	s_add_u32 s4, s8, 0x6648000
	v_writelane_b32 v255, s12, 0
	s_addc_u32 s84, s9, 0
	s_lshl_b64 s[0:1], s[0:1], 2
	v_writelane_b32 v255, s13, 1
	s_add_u32 s0, s4, s0
	v_writelane_b32 v255, s0, 2
	s_addc_u32 s0, s84, s1
	s_add_u32 s85, s8, 0x13fca000
	s_addc_u32 s79, s9, 0
	v_writelane_b32 v254, s11, 35
	v_writelane_b32 v255, s0, 3
	s_add_u32 s0, s85, s6
	v_writelane_b32 v255, s0, 4
	s_addc_u32 s0, s79, 0
	v_readlane_b32 s10, v254, 38
	v_writelane_b32 v255, s0, 5
	v_readlane_b32 s11, v254, 39
	s_add_u32 s0, s10, 0x9800000
	v_writelane_b32 v255, s0, 6
	s_addc_u32 s0, s11, 0
	s_mul_i32 s5, s5, 0x1e00000
	v_writelane_b32 v255, s0, 7
	v_readlane_b32 s0, v254, 36
	v_readlane_b32 s1, v254, 37
	s_add_u32 s0, s0, s5
	s_addc_u32 s1, s1, 0
	s_add_u32 s80, s8, 0x126ca000
	s_addc_u32 s81, s9, 0
	s_mov_b32 s55, s4
	s_add_u32 s4, s80, s6
	v_writelane_b32 v255, s4, 8
	s_addc_u32 s4, s81, 0
	v_writelane_b32 v255, s4, 9
	s_add_u32 s4, s0, 0x500000
	s_addc_u32 s5, s1, 0
	v_writelane_b32 v255, s4, 10
	s_mov_b32 s54, s47
	s_nop 0
	v_writelane_b32 v255, s5, 11
	s_add_u32 s4, s0, 0xa00000
	s_addc_u32 s5, s1, 0
	v_writelane_b32 v255, s4, 12
	s_nop 1
	v_writelane_b32 v255, s5, 13
	s_add_u32 s4, s0, 0x1400000
	s_addc_u32 s5, s1, 0
	v_writelane_b32 v255, s4, 14
	s_nop 1
	v_writelane_b32 v255, s5, 15
	s_add_u32 s4, s0, 0x1900000
	s_addc_u32 s5, s1, 0
	v_writelane_b32 v255, s4, 16
	s_nop 1
	v_writelane_b32 v255, s5, 17
	s_add_u32 s4, s0, 0xf00000
	v_writelane_b32 v255, s0, 18
	s_addc_u32 s5, s1, 0
	s_nop 0
	v_writelane_b32 v255, s1, 19
	v_writelane_b32 v255, s4, 20
	s_add_u32 s0, s10, 0x8800000
	s_nop 0
	v_writelane_b32 v255, s5, 21
	v_writelane_b32 v255, s0, 22
	s_addc_u32 s0, s11, 0
	v_writelane_b32 v255, s0, 23
	s_and_b64 s[0:1], s[36:37], exec
	s_movk_i32 s0, 0xa80
	s_cselect_b32 s0, s0, 0xb80
	v_writelane_b32 v255, s0, 24
	s_add_i32 s0, s78, 0x4200
	v_writelane_b32 v255, s0, 25
	v_readlane_b32 s4, v252, 0
	s_branch .LBB0_230

.LBB0_459:
	v_add_u32_e32 v250, 1, v250
	v_readlane_b32 s5, v252, 0
	s_nop 0
	v_readfirstlane_b32 s6, v250
	s_movk_i32 s4, 0x280
	s_cmp_lt_u32 s5, 64
	s_cbranch_scc1 .Lsch_done
	s_cmpk_lt_u32 s5, 0xc0
	s_cbranch_scc0 .Lsch_h
	s_sub_u32 s8, s5, 64
	s_cmp_lt_u32 s8, 64
	s_cbranch_scc0 .Lsch_rca
	s_cmp_eq_u32 s6, 1
	s_cbranch_scc0 .Lsch_done
	s_addk_i32 s8, 0x140
	s_mov_b32 s4, s8
	s_branch .Lsch_done
.Lsch_rca:
	s_cmp_le_u32 s6, 3
	s_cbranch_scc0 .Lsch_done
	s_sub_u32 s8, s8, 64
	s_mul_i32 s8, s8, 3
	s_add_u32 s8, s8, s6
	s_addk_i32 s8, 0x17f
	s_mov_b32 s4, s8
	s_branch .Lsch_done
.Lsch_h:
	s_sub_u32 s8, s5, 0xc0
	s_cmp_eq_u32 s6, 1
	s_cbranch_scc0 .Lsch_h2
	s_addk_i32 s8, 0x100
	s_mov_b32 s4, s8
	s_branch .Lsch_done
.Lsch_h2:
	s_cmp_eq_u32 s6, 2
	s_cbranch_scc0 .Lsch_done
	s_addk_i32 s8, 0x240
	s_mov_b32 s4, s8
.Lsch_done:
	s_mov_b64 s[0:1], 0
	s_branch .LBB0_229
